# hy_conv short-sequence items: both position tiles in one tap loop sharing the filter fragment; the separate unrolled second-tile MFMA chain is skipped
# speedup vs baseline: 1.1161x; 1.0000x over previous
.LBB0_705:
	s_cmp_eq_u32 s73, 64
	s_cbranch_scc1 .Lconv_lat2
	s_branch .Lconv_ctx2
	v_mov_b32_e32 v221, 0x11040
	v_cmp_gt_u32_e32 vcc, s73, v32
	v_lshl_add_u32 v220, v33, 1, v121
	s_nop 1
	v_cndmask_b32_e32 v220, v221, v220, vcc
	ds_read2_b32 v[36:37], v34 offset1:1
	ds_read2_b32 v[38:39], v34 offset0:2 offset1:3
	ds_read_b128 v[40:43], v220
	ds_read_b128 v[44:47], v220 offset:32
	ds_read2_b32 v[200:201], v34 offset0:8 offset1:9
	ds_read2_b32 v[202:203], v34 offset0:10 offset1:11

.Lconv_ctx2:
	v_sub_u32_e32 v212, v61, v35
	s_nop 0
	v_readfirstlane_b32 s100, v212
	v_add_u32_e32 v213, 0xa00, v121
	s_max_i32 s100, s100, 1
	s_min_i32 s100, s100, 0x100
	v_mov_b32_e32 v221, 0x11040
	v_mov_b32_e32 v16, 0
	v_mov_b32_e32 v17, 0
	v_mov_b32_e32 v18, 0
	v_mov_b32_e32 v19, 0
	v_mov_b32_e32 v20, 0
	v_mov_b32_e32 v21, 0
	v_mov_b32_e32 v22, 0
	v_mov_b32_e32 v23, 0
	v_mov_b32_e32 v24, 0
	v_mov_b32_e32 v25, 0
	v_mov_b32_e32 v26, 0
	v_mov_b32_e32 v27, 0
	v_mov_b32_e32 v28, 0
	v_mov_b32_e32 v29, 0
	v_mov_b32_e32 v30, 0
	v_mov_b32_e32 v31, 0
.Lcc2_loop:
	v_cmp_gt_u32_e32 vcc, s73, v32
	v_lshl_add_u32 v220, v33, 1, v121
	v_lshl_add_u32 v212, v33, 1, v213
	ds_read2_b32 v[36:37], v34 offset1:1
	ds_read2_b32 v[38:39], v34 offset0:2 offset1:3
	ds_read2_b32 v[200:201], v34 offset0:8 offset1:9
	ds_read2_b32 v[202:203], v34 offset0:10 offset1:11
	v_cndmask_b32_e32 v220, v221, v220, vcc
	v_cndmask_b32_e32 v212, v221, v212, vcc
	ds_read_b128 v[40:43], v220
	ds_read_b128 v[44:47], v220 offset:32
	ds_read_b128 v[204:207], v212
	ds_read_b128 v[208:211], v212 offset:32
	v_add_u32_e32 v32, -1, v32
	v_subrev_u32_e32 v33, 40, v33
	v_subrev_u32_e32 v34, 64, v34
	s_waitcnt lgkmcnt(0)
	v_mfma_f32_32x32x16_bf16 v[0:15], v[36:39], v[40:43], v[0:15]
	v_mfma_f32_32x32x16_bf16 v[16:31], v[36:39], v[204:207], v[16:31]
	v_mfma_f32_32x32x16_bf16 v[0:15], v[200:203], v[44:47], v[0:15]
	v_mfma_f32_32x32x16_bf16 v[16:31], v[200:203], v[208:211], v[16:31]
	s_add_i32 s100, s100, -1
	s_cmp_lg_u32 s100, 0
	s_cbranch_scc1 .Lcc2_loop
	s_branch .Lconv_exit
.Lconv_exit:
	s_waitcnt lgkmcnt(0)
	s_or_b64 exec, exec, s[10:11]
	s_and_b64 s[4:5], s[8:9], exec
	s_cselect_b32 s4, s76, 0x9000
	v_lshl_add_u32 v32, v60, 1, s4
	ds_read2_b64 v[40:43], v32 offset1:2
	ds_read2_b64 v[32:35], v32 offset0:4 offset1:6
	ds_read2_b64 v[44:47], v55 offset1:2
	ds_read2_b64 v[36:39], v55 offset0:4 offset1:6
	s_waitcnt vmcnt(0)
	v_mov_b32_e32 v73, v72
	s_and_b64 vcc, exec, s[36:37]
	s_cbranch_vccz .LBB0_708
	s_branch .Lcv_chain_skip
	ds_read2_b32 v[16:17], v123 offset0:112 offset1:113
	ds_read2_b32 v[18:19], v123 offset0:114 offset1:115
	ds_read_b128 v[20:23], v122 offset:2048
	ds_read_b128 v[48:51], v122 offset:2080
	ds_read2_b32 v[170:171], v123 offset0:120 offset1:121
	ds_read2_b32 v[172:173], v123 offset0:122 offset1:123
	s_waitcnt lgkmcnt(3)
	v_cndmask_b32_e64 v23, 0, v23, s[40:41]
	v_cndmask_b32_e64 v22, 0, v22, s[40:41]
	v_cndmask_b32_e64 v21, 0, v21, s[40:41]
	v_cndmask_b32_e64 v20, 0, v20, s[40:41]
	s_waitcnt lgkmcnt(2)
	v_cndmask_b32_e64 v51, 0, v51, s[40:41]
	v_cndmask_b32_e64 v50, 0, v50, s[40:41]
	v_mfma_f32_32x32x16_bf16 v[16:31], v[16:19], v[20:23], 0
	v_cndmask_b32_e64 v49, 0, v49, s[40:41]
	v_cndmask_b32_e64 v48, 0, v48, s[40:41]
	s_waitcnt lgkmcnt(0)
	s_nop 0
	v_mfma_f32_32x32x16_bf16 v[16:31], v[170:173], v[48:51], v[16:31]
	ds_read2_b32 v[48:49], v123 offset0:96 offset1:97
	ds_read2_b32 v[50:51], v123 offset0:98 offset1:99
	ds_read_b128 v[170:173], v124 offset:2048
	ds_read_b128 v[232:235], v124 offset:2080
	s_waitcnt lgkmcnt(1)
	v_cndmask_b32_e64 v173, 0, v173, s[42:43]
	v_cndmask_b32_e64 v172, 0, v172, s[42:43]
	v_cndmask_b32_e64 v171, 0, v171, s[42:43]
	v_cndmask_b32_e64 v170, 0, v170, s[42:43]
	s_nop 1
	v_mfma_f32_32x32x16_bf16 v[16:31], v[48:51], v[170:173], v[16:31]
	ds_read2_b32 v[48:49], v123 offset0:104 offset1:105
	ds_read2_b32 v[50:51], v123 offset0:106 offset1:107
	s_waitcnt lgkmcnt(2)
	v_cndmask_b32_e64 v173, 0, v235, s[42:43]
	v_cndmask_b32_e64 v172, 0, v234, s[42:43]
	v_cndmask_b32_e64 v171, 0, v233, s[42:43]
	v_cndmask_b32_e64 v170, 0, v232, s[42:43]
	s_waitcnt lgkmcnt(0)
	s_nop 0
	v_mfma_f32_32x32x16_bf16 v[16:31], v[48:51], v[170:173], v[16:31]
	ds_read2_b32 v[48:49], v123 offset0:80 offset1:81
	ds_read2_b32 v[50:51], v123 offset0:82 offset1:83
	ds_read_b128 v[170:173], v125 offset:2048
	ds_read_b128 v[232:235], v125 offset:2080
	s_waitcnt lgkmcnt(1)
	v_cndmask_b32_e64 v173, 0, v173, s[44:45]
	v_cndmask_b32_e64 v172, 0, v172, s[44:45]
	v_cndmask_b32_e64 v171, 0, v171, s[44:45]
	v_cndmask_b32_e64 v170, 0, v170, s[44:45]
	s_nop 1
	v_mfma_f32_32x32x16_bf16 v[16:31], v[48:51], v[170:173], v[16:31]
	ds_read2_b32 v[48:49], v123 offset0:88 offset1:89
	ds_read2_b32 v[50:51], v123 offset0:90 offset1:91
	s_waitcnt lgkmcnt(2)
	v_cndmask_b32_e64 v173, 0, v235, s[44:45]
	v_cndmask_b32_e64 v172, 0, v234, s[44:45]
	v_cndmask_b32_e64 v171, 0, v233, s[44:45]
	v_cndmask_b32_e64 v170, 0, v232, s[44:45]
	s_waitcnt lgkmcnt(0)
	s_nop 0
	v_mfma_f32_32x32x16_bf16 v[16:31], v[48:51], v[170:173], v[16:31]
	ds_read2_b32 v[48:49], v123 offset0:64 offset1:65
	ds_read2_b32 v[50:51], v123 offset0:66 offset1:67
	ds_read_b128 v[170:173], v126 offset:2048
	ds_read_b128 v[232:235], v126 offset:2080
	s_waitcnt lgkmcnt(1)
	v_cndmask_b32_e64 v173, 0, v173, s[46:47]
	v_cndmask_b32_e64 v172, 0, v172, s[46:47]
	v_cndmask_b32_e64 v171, 0, v171, s[46:47]
	v_cndmask_b32_e64 v170, 0, v170, s[46:47]
	s_nop 1
	v_mfma_f32_32x32x16_bf16 v[16:31], v[48:51], v[170:173], v[16:31]
	ds_read2_b32 v[48:49], v123 offset0:72 offset1:73
	ds_read2_b32 v[50:51], v123 offset0:74 offset1:75
	s_waitcnt lgkmcnt(2)
	v_cndmask_b32_e64 v173, 0, v235, s[46:47]
	v_cndmask_b32_e64 v172, 0, v234, s[46:47]
	v_cndmask_b32_e64 v171, 0, v233, s[46:47]
	v_cndmask_b32_e64 v170, 0, v232, s[46:47]
	s_waitcnt lgkmcnt(0)
	s_nop 0
	v_mfma_f32_32x32x16_bf16 v[16:31], v[48:51], v[170:173], v[16:31]
	ds_read2_b32 v[48:49], v123 offset0:48 offset1:49
	ds_read2_b32 v[50:51], v123 offset0:50 offset1:51
	ds_read_b128 v[170:173], v127 offset:2048
	ds_read_b128 v[232:235], v127 offset:2080
	s_waitcnt lgkmcnt(1)
	v_cndmask_b32_e64 v173, 0, v173, s[48:49]
	v_cndmask_b32_e64 v172, 0, v172, s[48:49]
	v_cndmask_b32_e64 v171, 0, v171, s[48:49]
	v_cndmask_b32_e64 v170, 0, v170, s[48:49]
	s_nop 1
	v_mfma_f32_32x32x16_bf16 v[16:31], v[48:51], v[170:173], v[16:31]
	ds_read2_b32 v[48:49], v123 offset0:56 offset1:57
	ds_read2_b32 v[50:51], v123 offset0:58 offset1:59
	s_waitcnt lgkmcnt(2)
	v_cndmask_b32_e64 v173, 0, v235, s[48:49]
	v_cndmask_b32_e64 v172, 0, v234, s[48:49]
	v_cndmask_b32_e64 v171, 0, v233, s[48:49]
	v_cndmask_b32_e64 v170, 0, v232, s[48:49]
	s_waitcnt lgkmcnt(0)
	s_nop 0
	v_mfma_f32_32x32x16_bf16 v[16:31], v[48:51], v[170:173], v[16:31]
	ds_read2_b32 v[48:49], v123 offset0:32 offset1:33
	ds_read2_b32 v[50:51], v123 offset0:34 offset1:35
	ds_read_b128 v[170:173], v128 offset:2048
	ds_read_b128 v[232:235], v128 offset:2080
	s_waitcnt lgkmcnt(1)
	v_cndmask_b32_e64 v173, 0, v173, s[50:51]
	v_cndmask_b32_e64 v172, 0, v172, s[50:51]
	v_cndmask_b32_e64 v171, 0, v171, s[50:51]
	v_cndmask_b32_e64 v170, 0, v170, s[50:51]
	s_nop 1
	v_mfma_f32_32x32x16_bf16 v[16:31], v[48:51], v[170:173], v[16:31]
	ds_read2_b32 v[48:49], v123 offset0:40 offset1:41
	ds_read2_b32 v[50:51], v123 offset0:42 offset1:43
	s_waitcnt lgkmcnt(2)
	v_cndmask_b32_e64 v173, 0, v235, s[50:51]
	v_cndmask_b32_e64 v172, 0, v234, s[50:51]
	v_cndmask_b32_e64 v171, 0, v233, s[50:51]
	v_cndmask_b32_e64 v170, 0, v232, s[50:51]
	s_waitcnt lgkmcnt(0)
	s_nop 0
	v_mfma_f32_32x32x16_bf16 v[16:31], v[48:51], v[170:173], v[16:31]
	ds_read2_b32 v[48:49], v123 offset0:16 offset1:17
	ds_read2_b32 v[50:51], v123 offset0:18 offset1:19
	ds_read_b128 v[170:173], v129 offset:2048
	ds_read_b128 v[232:235], v129 offset:2080
	s_waitcnt lgkmcnt(1)
	v_cndmask_b32_e64 v173, 0, v173, s[52:53]
	v_cndmask_b32_e64 v172, 0, v172, s[52:53]
	v_cndmask_b32_e64 v171, 0, v171, s[52:53]
	v_cndmask_b32_e64 v170, 0, v170, s[52:53]
	s_nop 1
	v_mfma_f32_32x32x16_bf16 v[16:31], v[48:51], v[170:173], v[16:31]
	ds_read2_b32 v[48:49], v123 offset0:24 offset1:25
	ds_read2_b32 v[50:51], v123 offset0:26 offset1:27
	s_waitcnt lgkmcnt(2)
	v_cndmask_b32_e64 v173, 0, v235, s[52:53]
	v_cndmask_b32_e64 v172, 0, v234, s[52:53]
	v_cndmask_b32_e64 v171, 0, v233, s[52:53]
	v_cndmask_b32_e64 v170, 0, v232, s[52:53]
	s_waitcnt lgkmcnt(0)
	s_nop 0
	v_mfma_f32_32x32x16_bf16 v[16:31], v[48:51], v[170:173], v[16:31]
	ds_read2_b32 v[48:49], v123 offset1:1
	ds_read2_b32 v[50:51], v123 offset0:2 offset1:3
	ds_read_b128 v[170:173], v130 offset:2048
	ds_read_b128 v[232:235], v130 offset:2080
	s_waitcnt lgkmcnt(1)
	v_cndmask_b32_e64 v173, 0, v173, s[54:55]
	v_cndmask_b32_e64 v172, 0, v172, s[54:55]
	v_cndmask_b32_e64 v171, 0, v171, s[54:55]
	v_cndmask_b32_e64 v170, 0, v170, s[54:55]
	s_nop 1
	v_mfma_f32_32x32x16_bf16 v[16:31], v[48:51], v[170:173], v[16:31]
	ds_read2_b32 v[48:49], v123 offset0:8 offset1:9
	ds_read2_b32 v[50:51], v123 offset0:10 offset1:11
	s_waitcnt lgkmcnt(2)
	v_cndmask_b32_e64 v173, 0, v235, s[54:55]
	v_cndmask_b32_e64 v172, 0, v234, s[54:55]
	v_cndmask_b32_e64 v171, 0, v233, s[54:55]
	v_cndmask_b32_e64 v170, 0, v232, s[54:55]
	s_waitcnt lgkmcnt(0)
	s_nop 0
	v_mfma_f32_32x32x16_bf16 v[16:31], v[48:51], v[170:173], v[16:31]
	ds_read2_b32 v[48:49], v132 offset1:1
	ds_read2_b32 v[50:51], v133 offset1:1
	ds_read_b128 v[170:173], v131 offset:2048
	ds_read_b128 v[232:235], v131 offset:2080
	s_waitcnt lgkmcnt(1)
	v_cndmask_b32_e64 v173, 0, v173, s[56:57]
	v_cndmask_b32_e64 v172, 0, v172, s[56:57]
	v_cndmask_b32_e64 v171, 0, v171, s[56:57]
	v_cndmask_b32_e64 v170, 0, v170, s[56:57]
	s_nop 1
	v_mfma_f32_32x32x16_bf16 v[16:31], v[48:51], v[170:173], v[16:31]
	ds_read2_b32 v[48:49], v134 offset1:1
	ds_read2_b32 v[50:51], v135 offset1:1
	s_waitcnt lgkmcnt(2)
	v_cndmask_b32_e64 v173, 0, v235, s[56:57]
	v_cndmask_b32_e64 v172, 0, v234, s[56:57]
	v_cndmask_b32_e64 v171, 0, v233, s[56:57]
	v_cndmask_b32_e64 v170, 0, v232, s[56:57]
	s_waitcnt lgkmcnt(0)
	s_nop 0
	v_mfma_f32_32x32x16_bf16 v[16:31], v[48:51], v[170:173], v[16:31]
	ds_read2_b32 v[48:49], v137 offset1:1
	ds_read2_b32 v[50:51], v138 offset1:1
	ds_read_b128 v[170:173], v136 offset:2048
	ds_read_b128 v[232:235], v136 offset:2080
	s_waitcnt lgkmcnt(1)
	v_cndmask_b32_e64 v173, 0, v173, s[58:59]
	v_cndmask_b32_e64 v172, 0, v172, s[58:59]
	v_cndmask_b32_e64 v171, 0, v171, s[58:59]
	v_cndmask_b32_e64 v170, 0, v170, s[58:59]
	s_nop 1
	v_mfma_f32_32x32x16_bf16 v[16:31], v[48:51], v[170:173], v[16:31]
	ds_read2_b32 v[48:49], v139 offset1:1
	ds_read2_b32 v[50:51], v140 offset1:1
	s_waitcnt lgkmcnt(2)
	v_cndmask_b32_e64 v173, 0, v235, s[58:59]
	v_cndmask_b32_e64 v172, 0, v234, s[58:59]
	v_cndmask_b32_e64 v171, 0, v233, s[58:59]
	v_cndmask_b32_e64 v170, 0, v232, s[58:59]
	s_waitcnt lgkmcnt(0)
	s_nop 0
	v_mfma_f32_32x32x16_bf16 v[16:31], v[48:51], v[170:173], v[16:31]
	ds_read2_b32 v[48:49], v142 offset1:1
	ds_read2_b32 v[50:51], v143 offset1:1
	ds_read_b128 v[170:173], v141 offset:2048
	ds_read_b128 v[232:235], v141 offset:2080
	s_waitcnt lgkmcnt(1)
	v_cndmask_b32_e64 v173, 0, v173, s[60:61]
	v_cndmask_b32_e64 v172, 0, v172, s[60:61]
	v_cndmask_b32_e64 v171, 0, v171, s[60:61]
	v_cndmask_b32_e64 v170, 0, v170, s[60:61]
	s_nop 1
	v_mfma_f32_32x32x16_bf16 v[16:31], v[48:51], v[170:173], v[16:31]
	ds_read2_b32 v[48:49], v144 offset1:1
	ds_read2_b32 v[50:51], v145 offset1:1
	s_waitcnt lgkmcnt(2)
	v_cndmask_b32_e64 v173, 0, v235, s[60:61]
	v_cndmask_b32_e64 v172, 0, v234, s[60:61]
	v_cndmask_b32_e64 v171, 0, v233, s[60:61]
	v_cndmask_b32_e64 v170, 0, v232, s[60:61]
	s_waitcnt lgkmcnt(0)
	s_nop 0
	v_mfma_f32_32x32x16_bf16 v[16:31], v[48:51], v[170:173], v[16:31]
	ds_read2_b32 v[48:49], v147 offset1:1
	ds_read2_b32 v[50:51], v148 offset1:1
	ds_read_b128 v[170:173], v146 offset:2048
	ds_read_b128 v[232:235], v146 offset:2080
	s_waitcnt lgkmcnt(1)
	v_cndmask_b32_e64 v173, 0, v173, s[62:63]
	v_cndmask_b32_e64 v172, 0, v172, s[62:63]
	v_cndmask_b32_e64 v171, 0, v171, s[62:63]
	v_cndmask_b32_e64 v170, 0, v170, s[62:63]
	s_nop 1
	v_mfma_f32_32x32x16_bf16 v[16:31], v[48:51], v[170:173], v[16:31]
	ds_read2_b32 v[48:49], v149 offset1:1
	ds_read2_b32 v[50:51], v150 offset1:1
	s_waitcnt lgkmcnt(2)
	v_cndmask_b32_e64 v173, 0, v235, s[62:63]
	v_cndmask_b32_e64 v172, 0, v234, s[62:63]
	v_cndmask_b32_e64 v171, 0, v233, s[62:63]
	v_cndmask_b32_e64 v170, 0, v232, s[62:63]
	s_waitcnt lgkmcnt(0)
	s_nop 0
	v_mfma_f32_32x32x16_bf16 v[16:31], v[48:51], v[170:173], v[16:31]
	ds_read2_b32 v[48:49], v152 offset1:1
	ds_read2_b32 v[50:51], v153 offset1:1
	ds_read_b128 v[170:173], v151 offset:2048
	ds_read_b128 v[232:235], v151 offset:2080
	s_waitcnt lgkmcnt(1)
	v_cndmask_b32_e64 v173, 0, v173, s[64:65]
	v_cndmask_b32_e64 v172, 0, v172, s[64:65]
	v_cndmask_b32_e64 v171, 0, v171, s[64:65]
	v_cndmask_b32_e64 v170, 0, v170, s[64:65]
	s_nop 1
	v_mfma_f32_32x32x16_bf16 v[16:31], v[48:51], v[170:173], v[16:31]
	ds_read2_b32 v[48:49], v154 offset1:1
	ds_read2_b32 v[50:51], v155 offset1:1
	s_waitcnt lgkmcnt(2)
	v_cndmask_b32_e64 v173, 0, v235, s[64:65]
	v_cndmask_b32_e64 v172, 0, v234, s[64:65]
	v_cndmask_b32_e64 v171, 0, v233, s[64:65]
	v_cndmask_b32_e64 v170, 0, v232, s[64:65]
	s_waitcnt lgkmcnt(0)
	s_nop 0
	v_mfma_f32_32x32x16_bf16 v[16:31], v[48:51], v[170:173], v[16:31]
	ds_read2_b32 v[48:49], v157 offset1:1
	ds_read2_b32 v[50:51], v158 offset1:1
	ds_read_b128 v[170:173], v156 offset:2048
	ds_read_b128 v[232:235], v156 offset:2080
	s_waitcnt lgkmcnt(1)
	v_cndmask_b32_e64 v173, 0, v173, s[66:67]
	v_cndmask_b32_e64 v172, 0, v172, s[66:67]
	v_cndmask_b32_e64 v171, 0, v171, s[66:67]
	v_cndmask_b32_e64 v170, 0, v170, s[66:67]
	s_nop 1
	v_mfma_f32_32x32x16_bf16 v[16:31], v[48:51], v[170:173], v[16:31]
	ds_read2_b32 v[48:49], v159 offset1:1
	ds_read2_b32 v[50:51], v160 offset1:1
	s_waitcnt lgkmcnt(2)
	v_cndmask_b32_e64 v173, 0, v235, s[66:67]
	v_cndmask_b32_e64 v172, 0, v234, s[66:67]
	v_cndmask_b32_e64 v171, 0, v233, s[66:67]
	v_cndmask_b32_e64 v170, 0, v232, s[66:67]
	s_waitcnt lgkmcnt(0)
	s_nop 0
	v_mfma_f32_32x32x16_bf16 v[16:31], v[48:51], v[170:173], v[16:31]
	ds_read2_b32 v[48:49], v162 offset1:1
	ds_read2_b32 v[50:51], v163 offset1:1
	ds_read_b128 v[170:173], v161 offset:2048
	ds_read_b128 v[232:235], v161 offset:2080
	s_waitcnt lgkmcnt(1)
	v_cndmask_b32_e64 v173, 0, v173, s[68:69]
	v_cndmask_b32_e64 v172, 0, v172, s[68:69]
	v_cndmask_b32_e64 v171, 0, v171, s[68:69]
	v_cndmask_b32_e64 v170, 0, v170, s[68:69]
	s_nop 1
	v_mfma_f32_32x32x16_bf16 v[16:31], v[48:51], v[170:173], v[16:31]
	ds_read2_b32 v[48:49], v164 offset1:1
	ds_read2_b32 v[50:51], v165 offset1:1
	s_waitcnt lgkmcnt(2)
	v_cndmask_b32_e64 v173, 0, v235, s[68:69]
	v_cndmask_b32_e64 v172, 0, v234, s[68:69]
	v_cndmask_b32_e64 v171, 0, v233, s[68:69]
	v_cndmask_b32_e64 v170, 0, v232, s[68:69]
	s_waitcnt lgkmcnt(0)
	s_nop 0
	v_mfma_f32_32x32x16_bf16 v[16:31], v[48:51], v[170:173], v[16:31]
.Lcv_chain_skip:
	v_lshl_add_u32 v48, v54, 1, s4
	v_add_u32_e32 v48, 0x800, v48
	ds_read2_b64 v[170:173], v48 offset1:2
	ds_read2_b64 v[48:51], v48 offset0:4 offset1:6
	ds_read_b64 v[174:175], v84 offset:2048
	s_waitcnt lgkmcnt(2)
	v_lshlrev_b32_e32 v194, 16, v170
	v_and_b32_e32 v195, 0xffff0000, v170
	s_waitcnt lgkmcnt(0)
	v_lshlrev_b32_e32 v196, 16, v174
	v_and_b32_e32 v197, 0xffff0000, v174
	v_lshlrev_b32_e32 v174, 16, v175
	v_and_b32_e32 v175, 0xffff0000, v175
	v_lshlrev_b32_e32 v170, 16, v171
	v_and_b32_e32 v171, 0xffff0000, v171
	v_pk_fma_f32 v[18:19], v[72:73], v[174:175], v[18:19]
	v_pk_fma_f32 v[16:17], v[72:73], v[196:197], v[16:17]
	v_pk_mul_f32 v[18:19], v[18:19], v[170:171]
	ds_read_b64 v[170:171], v86 offset:2048
	v_pk_mul_f32 v[16:17], v[16:17], v[194:195]
	v_lshlrev_b32_e32 v174, 16, v172
	v_and_b32_e32 v175, 0xffff0000, v172
	v_lshlrev_b32_e32 v172, 16, v173
	s_waitcnt lgkmcnt(0)
	v_lshlrev_b32_e32 v194, 16, v170
	v_and_b32_e32 v195, 0xffff0000, v170
	v_lshlrev_b32_e32 v170, 16, v171
	v_and_b32_e32 v171, 0xffff0000, v171
	v_pk_fma_f32 v[22:23], v[72:73], v[170:171], v[22:23]
	ds_read_b64 v[170:171], v87 offset:2048
	v_pk_fma_f32 v[20:21], v[72:73], v[194:195], v[20:21]
	v_and_b32_e32 v173, 0xffff0000, v173
	v_pk_mul_f32 v[20:21], v[20:21], v[174:175]
	v_pk_mul_f32 v[22:23], v[22:23], v[172:173]
	s_waitcnt lgkmcnt(0)
	v_lshlrev_b32_e32 v174, 16, v170
	v_and_b32_e32 v175, 0xffff0000, v170
	v_lshlrev_b32_e32 v170, 16, v171
	v_and_b32_e32 v171, 0xffff0000, v171
	v_lshlrev_b32_e32 v172, 16, v48
	v_and_b32_e32 v173, 0xffff0000, v48
	v_lshlrev_b32_e32 v48, 16, v49
	v_and_b32_e32 v49, 0xffff0000, v49
	v_pk_fma_f32 v[26:27], v[72:73], v[170:171], v[26:27]
	v_pk_fma_f32 v[24:25], v[72:73], v[174:175], v[24:25]
	v_pk_mul_f32 v[26:27], v[26:27], v[48:49]
	ds_read_b64 v[48:49], v88 offset:2048
	v_pk_mul_f32 v[24:25], v[24:25], v[172:173]
	v_lshlrev_b32_e32 v170, 16, v50
	v_and_b32_e32 v171, 0xffff0000, v50
	v_lshlrev_b32_e32 v50, 16, v51
	s_waitcnt lgkmcnt(0)
	v_lshlrev_b32_e32 v172, 16, v48
	v_and_b32_e32 v173, 0xffff0000, v48
	v_lshlrev_b32_e32 v48, 16, v49
	v_and_b32_e32 v49, 0xffff0000, v49
	v_and_b32_e32 v51, 0xffff0000, v51
	v_pk_fma_f32 v[28:29], v[72:73], v[172:173], v[28:29]
	v_pk_fma_f32 v[30:31], v[72:73], v[48:49], v[30:31]
	v_pk_mul_f32 v[28:29], v[28:29], v[170:171]
	v_pk_mul_f32 v[30:31], v[30:31], v[50:51]
